# fused residual epilogue: residual-stream stores deferred past the row-statistics payload and arrival atomic (their drain overlaps the cross-workgroup wait)
# speedup vs baseline: 1.0012x; 1.0012x over previous
;     __device__ __forceinline__ void fused(f32x4 (&acc)[2][2][4][2], const Unit& u, int wr, int wc, int fr, int fq, ldsp lds, int wid, int lane) const {
;         const int rowt = u.pm * BM, b = rowt >> 11;
;         const char* xsb = (const char*)(xs + (size_t)rowt * D + u.pn * BM);
;         char* xdb = (char*)(xd + (size_t)rowt * D + u.pn * BM);
;         const char* gp = (const char*)(gate + (size_t)b * NMOD + u.pn * BM);
;         const unsigned coff = (unsigned)(wc * 32 + 4 * fq) * 4u;
;         unsigned off0 = (unsigned)(wr * 64 + fr) * (D * 4u) + coff; asm volatile("" : "+v"(off0));
; #pragma unroll
;         for (int bj = 0; bj < 2; ++bj)
; #pragma unroll
;             for (int n = 0; n < 2; ++n) { const f32x4 gv = *(const f32x4*)(gp + coff + (bj * HALF + n * 16) * 4);
; #pragma unroll
;                 for (int ai = 0; ai < 2; ++ai) {
; #pragma unroll
;                     for (int m = 0; m < 4; ++m) { const unsigned off = off0 + (unsigned)((ai * HALF + m * 16) * D + bj * HALF + n * 16) * 4u;
;                         const f32x4 xv = *(const f32x4*)(xsb + off); acc[ai][bj][m][n] = xv + gv * acc[ai][bj][m][n];
;                         if (!fin) *(f32x4*)(xdb + off) = acc[ai][bj][m][n]; }
;                     asm volatile("" ::: "memory"); } }
.LBB0_352:
	v_readlane_b32 s8, v255, 19
	s_lshl_b32 s5, s8, 2
	v_readlane_b32 s8, v254, 30
	s_add_u32 s5, s8, s5
	v_readlane_b32 s8, v254, 31
	v_readlane_b32 s9, v255, 20
	s_addc_u32 s24, s8, 0
	s_lshl_b32 s8, s3, 8
	s_ashr_i32 s9, s8, 31
	s_ashr_i32 s25, s3, 3
	s_lshl_b64 s[10:11], s[8:9], 12
	v_readlane_b32 s12, v254, 32
	v_readlane_b32 s13, v254, 33
	s_add_u32 s9, s12, s10
	s_addc_u32 s12, s13, s11
	s_lshl_b32 s14, s40, 8
	s_ashr_i32 s15, s14, 31
	s_lshl_b64 s[22:23], s[14:15], 2
	s_add_u32 s42, s9, s22
	s_addc_u32 s43, s12, s23
	s_add_u32 s9, s54, s10
	s_addc_u32 s10, s55, s11
	s_add_u32 s12, s9, s22
	s_addc_u32 s13, s10, s23
	s_mul_hi_i32 s11, s25, 0x1800
	s_mul_i32 s10, s25, 0x1800
	s_lshl_b64 s[30:31], s[10:11], 2
	v_lshl_or_b32 v149, s4, 5, v161
	s_add_u32 s5, s5, s30
	v_lshlrev_b32_e32 v146, 2, v149
	s_addc_u32 s9, s24, s31
	v_lshl_or_b32 v96, v148, 12, v146
	s_add_u32 s22, s5, s22
	s_addc_u32 s23, s9, s23
	s_mov_b64 s[100:101], s[12:13]
	v_add_u32_e32 v147, 0x10000, v96
	v_add_u32_e32 v194, 0x20000, v96
	v_add_u32_e32 v195, 0x30000, v96
	v_add_u32_e32 v197, 0x80000, v96
	v_add_u32_e32 v198, 0x90000, v96
	v_add_u32_e32 v199, 0xa0000, v96
	v_add_u32_e32 v200, 0xb0000, v96
	global_load_dwordx4 v[142:145], v146, s[22:23]
	global_load_dwordx4 v[150:153], v146, s[22:23] offset:64
	global_load_dwordx4 v[190:193], v146, s[22:23] offset:512
	global_load_dwordx4 v[162:165], v96, s[42:43]
	global_load_dwordx4 v[166:169], v147, s[42:43]
	global_load_dwordx4 v[170:173], v194, s[42:43]
	global_load_dwordx4 v[174:177], v195, s[42:43]
	global_load_dwordx4 v[178:181], v197, s[42:43]
	global_load_dwordx4 v[182:185], v198, s[42:43]
	global_load_dwordx4 v[226:229], v199, s[42:43]
	global_load_dwordx4 v[230:233], v200, s[42:43]
	global_load_dwordx4 v[234:237], v96, s[42:43] offset:64
	global_load_dwordx4 v[238:241], v147, s[42:43] offset:64
	global_load_dwordx4 v[242:245], v194, s[42:43] offset:64
	global_load_dwordx4 v[246:249], v195, s[42:43] offset:64
	global_load_dwordx4 v[250:253], v197, s[42:43] offset:64
	global_load_dwordx4 v[202:205], v198, s[42:43] offset:64
	global_load_dwordx4 v[206:209], v199, s[42:43] offset:64
	global_load_dwordx4 v[210:213], v200, s[42:43] offset:64
	s_waitcnt vmcnt(19)
	s_barrier
	v_cndmask_b32_e64 v134, 0, 1, s[84:85]
	v_cmp_ne_u32_e64 s[10:11], 1, v134
	v_readlane_b32 s36, v255, 14
	v_readlane_b32 s44, v255, 0
	s_mov_b32 s64, 0x41000000
	v_readlane_b32 s65, v254, 51
	v_readlane_b32 s37, v255, 15
	v_readlane_b32 s45, v255, 1
	s_andn2_b64 vcc, exec, s[84:85]
	s_cbranch_vccnz .Lrn_ladder_fin
;     __device__ __forceinline__ void fused(f32x4 (&acc)[2][2][4][2], const Unit& u, int wr, int wc, int fr, int fq, ldsp lds, int wid, int lane) const {
;     ...
; #pragma unroll
;         for (int bj = 0; bj < 2; ++bj)
; #pragma unroll
;             for (int n = 0; n < 2; ++n) { const f32x4 gv = *(const f32x4*)(gp + coff + (bj * HALF + n * 16) * 4);
; #pragma unroll
;                 for (int ai = 0; ai < 2; ++ai) {
; #pragma unroll
;                     for (int m = 0; m < 4; ++m) { const unsigned off = off0 + (unsigned)((ai * HALF + m * 16) * D + bj * HALF + n * 16) * 4u;
;                         const f32x4 xv = *(const f32x4*)(xsb + off); acc[ai][bj][m][n] = xv + gv * acc[ai][bj][m][n];
;                         if (!fin) *(f32x4*)(xdb + off) = acc[ai][bj][m][n]; }
;                     asm volatile("" ::: "memory"); } }
	s_waitcnt vmcnt(15)
	v_pk_fma_f32 v[140:141], v[128:129], v[144:145], v[164:165]
	v_pk_fma_f32 v[138:139], v[126:127], v[142:143], v[162:163]
	global_load_dwordx4 v[162:165], v96, s[42:43] offset:512
	s_waitcnt vmcnt(15)
	v_pk_fma_f32 v[136:137], v[124:125], v[144:145], v[168:169]
	v_pk_fma_f32 v[134:135], v[122:123], v[142:143], v[166:167]
	global_load_dwordx4 v[166:169], v147, s[42:43] offset:512
	s_waitcnt vmcnt(15)
	v_pk_fma_f32 v[132:133], v[116:117], v[144:145], v[172:173]
	v_pk_fma_f32 v[130:131], v[114:115], v[142:143], v[170:171]
	global_load_dwordx4 v[170:173], v194, s[42:43] offset:512
	s_waitcnt vmcnt(15)
	v_pk_fma_f32 v[128:129], v[108:109], v[144:145], v[176:177]
	v_pk_fma_f32 v[126:127], v[106:107], v[142:143], v[174:175]
	global_load_dwordx4 v[174:177], v195, s[42:43] offset:512
	s_waitcnt vmcnt(15)
	v_pk_fma_f32 v[124:125], v[100:101], v[144:145], v[180:181]
	v_pk_fma_f32 v[122:123], v[98:99], v[142:143], v[178:179]
	global_load_dwordx4 v[178:181], v197, s[42:43] offset:512
	s_waitcnt vmcnt(15)
	v_pk_fma_f32 v[116:117], v[90:91], v[144:145], v[184:185]
	v_pk_fma_f32 v[114:115], v[88:89], v[142:143], v[182:183]
	global_load_dwordx4 v[182:185], v198, s[42:43] offset:512
	s_waitcnt vmcnt(15)
	v_pk_fma_f32 v[108:109], v[82:83], v[144:145], v[228:229]
	v_pk_fma_f32 v[106:107], v[80:81], v[142:143], v[226:227]
	global_load_dwordx4 v[226:229], v199, s[42:43] offset:512
	s_waitcnt vmcnt(15)
	v_pk_fma_f32 v[100:101], v[74:75], v[144:145], v[232:233]
	v_pk_fma_f32 v[98:99], v[72:73], v[142:143], v[230:231]
	global_load_dwordx4 v[230:233], v200, s[42:43] offset:512
	global_load_dwordx4 v[142:145], v146, s[22:23] offset:576
	s_waitcnt vmcnt(16)
	v_pk_fma_f32 v[94:95], v[94:95], v[152:153], v[236:237]
	v_pk_fma_f32 v[92:93], v[92:93], v[150:151], v[234:235]
	global_load_dwordx4 v[234:237], v96, s[42:43] offset:576
	s_waitcnt vmcnt(16)
	v_pk_fma_f32 v[90:91], v[86:87], v[152:153], v[240:241]
	v_pk_fma_f32 v[88:89], v[84:85], v[150:151], v[238:239]
	global_load_dwordx4 v[238:241], v147, s[42:43] offset:576
	s_waitcnt vmcnt(16)
	v_pk_fma_f32 v[86:87], v[78:79], v[152:153], v[244:245]
	v_pk_fma_f32 v[84:85], v[76:77], v[150:151], v[242:243]
	global_load_dwordx4 v[242:245], v194, s[42:43] offset:576
	s_waitcnt vmcnt(16)
	v_pk_fma_f32 v[82:83], v[70:71], v[152:153], v[248:249]
	v_pk_fma_f32 v[80:81], v[68:69], v[150:151], v[246:247]
	global_load_dwordx4 v[246:249], v195, s[42:43] offset:576
	s_waitcnt vmcnt(16)
	v_pk_fma_f32 v[78:79], v[66:67], v[152:153], v[252:253]
	v_pk_fma_f32 v[76:77], v[64:65], v[150:151], v[250:251]
	global_load_dwordx4 v[250:253], v197, s[42:43] offset:576
	s_waitcnt vmcnt(16)
	v_pk_fma_f32 v[74:75], v[62:63], v[152:153], v[204:205]
	v_pk_fma_f32 v[72:73], v[60:61], v[150:151], v[202:203]
	global_load_dwordx4 v[202:205], v198, s[42:43] offset:576
	s_waitcnt vmcnt(16)
	v_pk_fma_f32 v[70:71], v[54:55], v[152:153], v[208:209]
	v_pk_fma_f32 v[68:69], v[52:53], v[150:151], v[206:207]
	global_load_dwordx4 v[206:209], v199, s[42:43] offset:576
	s_waitcnt vmcnt(16)
	v_pk_fma_f32 v[66:67], v[46:47], v[152:153], v[212:213]
	v_pk_fma_f32 v[64:65], v[44:45], v[150:151], v[210:211]
	global_load_dwordx4 v[210:213], v200, s[42:43] offset:576
	s_waitcnt vmcnt(16)
	v_pk_fma_f32 v[62:63], v[58:59], v[192:193], v[164:165]
	v_pk_fma_f32 v[60:61], v[56:57], v[190:191], v[162:163]
	s_waitcnt vmcnt(15)
	v_pk_fma_f32 v[58:59], v[50:51], v[192:193], v[168:169]
	v_pk_fma_f32 v[56:57], v[48:49], v[190:191], v[166:167]
	s_waitcnt vmcnt(14)
	v_pk_fma_f32 v[54:55], v[42:43], v[192:193], v[172:173]
	v_pk_fma_f32 v[52:53], v[40:41], v[190:191], v[170:171]
	s_waitcnt vmcnt(13)
	v_pk_fma_f32 v[50:51], v[38:39], v[192:193], v[176:177]
	v_pk_fma_f32 v[48:49], v[36:37], v[190:191], v[174:175]
	s_waitcnt vmcnt(12)
	v_pk_fma_f32 v[46:47], v[34:35], v[192:193], v[180:181]
	v_pk_fma_f32 v[44:45], v[32:33], v[190:191], v[178:179]
	s_waitcnt vmcnt(11)
	v_pk_fma_f32 v[42:43], v[30:31], v[192:193], v[184:185]
	v_pk_fma_f32 v[40:41], v[28:29], v[190:191], v[182:183]
	s_waitcnt vmcnt(10)
	v_pk_fma_f32 v[38:39], v[26:27], v[192:193], v[228:229]
	v_pk_fma_f32 v[36:37], v[24:25], v[190:191], v[226:227]
	s_waitcnt vmcnt(9)
	v_pk_fma_f32 v[34:35], v[22:23], v[192:193], v[232:233]
	v_pk_fma_f32 v[32:33], v[20:21], v[190:191], v[230:231]
	s_waitcnt vmcnt(7)
	v_pk_fma_f32 v[30:31], v[120:121], v[144:145], v[236:237]
	v_pk_fma_f32 v[28:29], v[118:119], v[142:143], v[234:235]
	s_waitcnt vmcnt(6)
	v_pk_fma_f32 v[26:27], v[112:113], v[144:145], v[240:241]
	v_pk_fma_f32 v[24:25], v[110:111], v[142:143], v[238:239]
	s_waitcnt vmcnt(5)
	v_pk_fma_f32 v[22:23], v[104:105], v[144:145], v[244:245]
	v_pk_fma_f32 v[20:21], v[102:103], v[142:143], v[242:243]
	s_waitcnt vmcnt(4)
	v_pk_fma_f32 v[18:19], v[18:19], v[144:145], v[248:249]
	v_pk_fma_f32 v[16:17], v[16:17], v[142:143], v[246:247]
	s_waitcnt vmcnt(3)
	v_pk_fma_f32 v[14:15], v[14:15], v[144:145], v[252:253]
	v_pk_fma_f32 v[12:13], v[12:13], v[142:143], v[250:251]
	s_waitcnt vmcnt(2)
	v_pk_fma_f32 v[10:11], v[10:11], v[144:145], v[204:205]
	v_pk_fma_f32 v[8:9], v[8:9], v[142:143], v[202:203]
	s_waitcnt vmcnt(1)
	v_pk_fma_f32 v[6:7], v[6:7], v[144:145], v[208:209]
	v_pk_fma_f32 v[4:5], v[4:5], v[142:143], v[206:207]
	s_waitcnt vmcnt(0)
	v_pk_fma_f32 v[2:3], v[2:3], v[144:145], v[212:213]
	v_pk_fma_f32 v[0:1], v[0:1], v[142:143], v[210:211]
	v_mov_b32_e32 v146, v96
	s_branch .Lrn_ladder_done

;     __device__ __forceinline__ void fused(f32x4 (&acc)[2][2][4][2], const Unit& u, int wr, int wc, int fr, int fq, ldsp lds, int wid, int lane) const {
;     ...
;                     for (int m = 0; m < 4; ++m) { const unsigned off = off0 + (unsigned)((ai * HALF + m * 16) * D + bj * HALF + n * 16) * 4u;
;                         const f32x4 xv = *(const f32x4*)(xsb + off); acc[ai][bj][m][n] = xv + gv * acc[ai][bj][m][n];
;                         if (!fin) *(f32x4*)(xdb + off) = acc[ai][bj][m][n]; }
;     ...
;         if (lane == 0) __hip_atomic_fetch_add(cnt + 64 * u.pm, 1u, __ATOMIC_RELAXED, __HIP_MEMORY_SCOPE_AGENT);
;         if (wid == 0) { unsigned sp = 0u;
;             while ((unsigned)__builtin_amdgcn_readfirstlane(__hip_atomic_load(cnt + 64 * u.pm, __ATOMIC_RELAXED, __HIP_MEMORY_SCOPE_AGENT)) < 32u) { __builtin_amdgcn_s_sleep(2); if (++sp > (1u << 22)) break; }
.LBB0_437:
	s_or_b64 exec, exec, s[12:13]
	s_and_b64 vcc, exec, s[84:85]
	s_cbranch_vccz .Lrn_defer_skip
	global_store_dwordx4 v146, v[138:141], s[100:101] nt
	global_store_dwordx4 v147, v[134:137], s[100:101] nt
	global_store_dwordx4 v194, v[130:133], s[100:101] nt
	global_store_dwordx4 v195, v[126:129], s[100:101] nt
	global_store_dwordx4 v197, v[122:125], s[100:101] nt
	global_store_dwordx4 v198, v[114:117], s[100:101] nt
	global_store_dwordx4 v199, v[106:109], s[100:101] nt
	global_store_dwordx4 v200, v[98:101], s[100:101] nt
	global_store_dwordx4 v146, v[92:95], s[100:101] offset:64 nt
	global_store_dwordx4 v147, v[88:91], s[100:101] offset:64 nt
	global_store_dwordx4 v194, v[84:87], s[100:101] offset:64 nt
	global_store_dwordx4 v195, v[80:83], s[100:101] offset:64 nt
	global_store_dwordx4 v197, v[76:79], s[100:101] offset:64 nt
	global_store_dwordx4 v198, v[72:75], s[100:101] offset:64 nt
	global_store_dwordx4 v199, v[68:71], s[100:101] offset:64 nt
	global_store_dwordx4 v200, v[64:67], s[100:101] offset:64 nt
	global_store_dwordx4 v146, v[60:63], s[100:101] offset:512 nt
	global_store_dwordx4 v147, v[56:59], s[100:101] offset:512 nt
	global_store_dwordx4 v194, v[52:55], s[100:101] offset:512 nt
	global_store_dwordx4 v195, v[48:51], s[100:101] offset:512 nt
	global_store_dwordx4 v197, v[44:47], s[100:101] offset:512 nt
	global_store_dwordx4 v198, v[40:43], s[100:101] offset:512 nt
	global_store_dwordx4 v199, v[36:39], s[100:101] offset:512 nt
	global_store_dwordx4 v200, v[32:35], s[100:101] offset:512 nt
	global_store_dwordx4 v146, v[28:31], s[100:101] offset:576 nt
	global_store_dwordx4 v147, v[24:27], s[100:101] offset:576 nt
	global_store_dwordx4 v194, v[20:23], s[100:101] offset:576 nt
	global_store_dwordx4 v195, v[16:19], s[100:101] offset:576 nt
	global_store_dwordx4 v197, v[12:15], s[100:101] offset:576 nt
	global_store_dwordx4 v198, v[8:11], s[100:101] offset:576 nt
	global_store_dwordx4 v199, v[4:7], s[100:101] offset:576 nt
	global_store_dwordx4 v200, v[0:3], s[100:101] offset:576 nt
.Lrn_defer_skip:
	s_cmp_gt_u32 s0, 63
	s_cbranch_scc1 .LBB0_447
	s_lshl_b32 s0, s3, 6
	s_ashr_i32 s1, s0, 31
	s_lshl_b64 s[0:1], s[0:1], 2
	v_readlane_b32 s3, v254, 60
	s_add_u32 s12, s3, s0
	v_readlane_b32 s0, v254, 61
	s_addc_u32 s13, s0, s1
	s_mov_b32 s0, 0x400001
	s_branch .LBB0_440
